# PROJ: rinv0 row scales for the epilogue requested at the top of the unit's first K-iteration (spare VGPRs), first two counted DMA waits 8->16
# baseline (speedup 1.0000x reference)
;     __device__ bool next(int i, Unit& u) const { if (r0 + i >= r1) return false; return base.next(r0 + i, u); }
;     __device__ bool next(int i, Unit& u) const { const int L = i * G + c; if (L >= 256) return false; u.pm = L; u.pn = L >> 3; return true; }
; #define PG8_STAGE(bufoff, gbase, voff) do { _Pragma("unroll") for (int _i = 0; _i < 2; ++_i) \
;         __builtin_amdgcn_global_load_lds((const unsigned*)((const char*)(gbase) + (voff)[_i]), (LAS unsigned*)(lds + (bufoff) + ldsw + _i * 8192), 16, 0, 0); } while (0)
; #define PG8_LDA(dst, b, h) do { _Pragma("unroll") for (int m = 0; m < 4; ++m) _Pragma("unroll") for (int k = 0; k < 2; ++k) dst[m][k] = *(const LAS bf16x8*)(lds + PG8_SA(b, h) + aoff + m * 2048 + k * 1024); } while (0)
; #define PG8_WAIT_V(n) asm volatile("s_waitcnt vmcnt(" #n ")" ::: "memory")
; #define PG8_WAIT_L(n) asm volatile("s_waitcnt lgkmcnt(" #n ")" ::: "memory")
; template <class Epi, class Sched>
; __device__ __forceinline__ void gemm_phase(LAS unsigned char* lds, const Gemm g, const Sched& S, const Epi& E, int wave_id) {
;     ...
;         const bool has_next = S.next(ui + 1, nxt);
;         const char* nA = has_next ? (const char*)g.A + (size_t)nxt.pm * tstepA : cA; const char* nB = has_next ? (const char*)g.Bt + (size_t)nxt.pn * tstepB : cB;
;         for (int t = 0; t < nt; t += 2) {
;             const bool last = (t == nt - 2);
;             const char* a1 = cA + (size_t)(t + 1) * kstep;
;             const char* a2 = last ? nA : cA + (size_t)(t + 2) * kstep; const char* b2 = last ? nB : cB + (size_t)(t + 2) * kstep;
;             const char* a3 = a2 + kstep; const char* b3 = b2 + kstep;
;             PG8_LDB(B0, 0, 0); PG8_LDB(B1, 0, 1); PG8_SCHED; PG8_LDA(At, 0, 0); PG8_STAGE(PG8_SA(1, 1), a1 + hstepA, voffA);
;             PG8_WAIT_V(8); PG8_WAIT_L(0); PG8_BAR; PG8_MMA(0, 0, At, B0); PG8_MMA(0, 1, At, B1); PG8_BAR; PG8_SCHED;
;             PG8_LDA(At, 0, 1); PG8_STAGE(PG8_SB(0, 0), b2, voffB); PG8_STAGE(PG8_SB(0, 1), b2 + hstepB, voffB); PG8_STAGE(PG8_SA(0, 0), a2, voffA);
;             PG8_WAIT_V(8); PG8_WAIT_L(0); PG8_BAR; PG8_MMA(1, 0, At, B0); PG8_MMA(1, 1, At, B1); PG8_BAR; PG8_SCHED;
;     __device__ __forceinline__ void load(Pre& p, const pg8::Unit& u, int ai, int m, int wr, int wc, int fr, int fq) const {
;     ...
;         if (MODE == EM_PROJ || MODE == EM_GATES) p.rs = ((const float*)(ws + WS_RINV0))[row];
.LBB0_251:
	s_ashr_i32 s45, s44, 31
	s_lshl_b64 s[14:15], s[44:45], 19
	s_add_u32 s46, s52, s14
	s_addc_u32 s47, s53, s15
	s_and_b64 s[14:15], s[4:5], exec
	s_cselect_b32 s2, s47, s11
	s_cselect_b32 s7, s46, s10
	s_ashr_i32 s39, s38, 31
	s_lshl_b64 s[14:15], s[38:39], 19
	s_add_u32 s48, s92, s14
	s_addc_u32 s49, s93, s15
	s_and_b64 s[14:15], s[4:5], exec
	s_cselect_b32 s9, s49, s13
	s_cselect_b32 s18, s48, s12
	s_add_u32 s10, s10, 0x40080
	s_addc_u32 s11, s11, 0
	s_add_u32 s33, s12, 0x100
	s_addc_u32 s39, s13, 0
	s_mov_b32 s45, -2
	s_lshl_b32 s14, s8, 8
	s_add_i32 s14, s14, s61
	v_or_b32_e32 v252, s14, v167
	v_ashrrev_i32_e32 v253, 31, v252
	v_lshl_add_u64 v[252:253], v[252:253], 2, s[26:27]
	global_load_dword v244, v[252:253], off
	global_load_dword v245, v[252:253], off offset:64
	global_load_dword v246, v[252:253], off offset:128
	global_load_dword v247, v[252:253], off offset:192
	global_load_dword v248, v[252:253], off offset:512
	global_load_dword v249, v[252:253], off offset:576
	global_load_dword v250, v[252:253], off offset:640
	global_load_dword v251, v[252:253], off offset:704
	ds_read_b128 v[16:19], v183
	ds_read_b128 v[20:23], v183 offset:1024
	ds_read_b128 v[32:35], v183 offset:2048
	ds_read_b128 v[36:39], v183 offset:3072
	ds_read_b128 v[184:187], v190
	ds_read_b128 v[194:197], v190 offset:1024
	ds_read_b128 v[198:201], v190 offset:2048
	ds_read_b128 v[202:205], v190 offset:3072
	s_add_u32 s12, s10, 0xfffc0080
	s_addc_u32 s13, s11, -1
	s_cmp_eq_u32 s45, 12
	s_cselect_b32 s15, s2, s13
	s_cselect_b32 s14, s7, s12
	s_cselect_b32 s13, s9, s39
	s_cselect_b32 s12, s18, s33
	v_lshl_add_u64 v[168:169], s[10:11], 0, v[158:159]
	s_add_i32 m0, s55, 0xc000
	ds_read_b128 v[206:209], v191
	ds_read_b128 v[210:213], v191 offset:1024
	ds_read_b128 v[214:217], v191 offset:2048
	ds_read_b128 v[218:221], v191 offset:3072
	ds_read_b128 v[222:225], v191 offset:4096
	ds_read_b128 v[226:229], v191 offset:5120
	ds_read_b128 v[230:233], v191 offset:6144
	ds_read_b128 v[234:237], v191 offset:7168
	global_load_lds_dwordx4 v[168:169], off
	v_lshl_add_u64 v[168:169], s[10:11], 0, v[160:161]
	s_add_i32 m0, s55, 0xe000
	s_nop 0
	global_load_lds_dwordx4 v[168:169], off
	s_waitcnt vmcnt(16)
	s_waitcnt lgkmcnt(0)
	s_barrier
	s_setprio 1
	s_waitcnt lgkmcnt(0)
	v_mfma_f32_16x16x32_bf16 v[140:143], v[16:19], v[206:209], 0
	v_mfma_f32_16x16x32_bf16 v[136:139], v[32:35], v[206:209], 0
	v_mfma_f32_16x16x32_bf16 v[124:127], v[16:19], v[214:217], 0
	v_mfma_f32_16x16x32_bf16 v[120:123], v[32:35], v[214:217], 0
	v_mfma_f32_16x16x32_bf16 v[108:111], v[16:19], v[222:225], 0
	v_mfma_f32_16x16x32_bf16 v[104:107], v[32:35], v[222:225], 0
	v_mfma_f32_16x16x32_bf16 v[92:95], v[16:19], v[230:233], 0
	v_mfma_f32_16x16x32_bf16 v[88:91], v[32:35], v[230:233], 0
	v_mfma_f32_16x16x32_bf16 v[140:143], v[20:23], v[210:213], v[140:143]
	v_mfma_f32_16x16x32_bf16 v[136:139], v[36:39], v[210:213], v[136:139]
	v_mfma_f32_16x16x32_bf16 v[124:127], v[20:23], v[218:221], v[124:127]
	v_mfma_f32_16x16x32_bf16 v[120:123], v[36:39], v[218:221], v[120:123]
	v_mfma_f32_16x16x32_bf16 v[108:111], v[20:23], v[226:229], v[108:111]
	v_mfma_f32_16x16x32_bf16 v[104:107], v[36:39], v[226:229], v[104:107]
	v_mfma_f32_16x16x32_bf16 v[92:95], v[20:23], v[234:237], v[92:95]
	v_mfma_f32_16x16x32_bf16 v[88:91], v[36:39], v[234:237], v[88:91]
	s_setprio 0
	s_setprio 1
	v_mfma_f32_16x16x32_bf16 v[132:135], v[184:187], v[206:209], 0
	v_mfma_f32_16x16x32_bf16 v[128:131], v[198:201], v[206:209], 0
	v_mfma_f32_16x16x32_bf16 v[116:119], v[184:187], v[214:217], 0
	v_mfma_f32_16x16x32_bf16 v[112:115], v[198:201], v[214:217], 0
	v_mfma_f32_16x16x32_bf16 v[100:103], v[184:187], v[222:225], 0
	v_mfma_f32_16x16x32_bf16 v[96:99], v[198:201], v[222:225], 0
	v_mfma_f32_16x16x32_bf16 v[84:87], v[184:187], v[230:233], 0
	v_mfma_f32_16x16x32_bf16 v[80:83], v[198:201], v[230:233], 0
	v_mfma_f32_16x16x32_bf16 v[132:135], v[194:197], v[210:213], v[132:135]
	v_mfma_f32_16x16x32_bf16 v[128:131], v[202:205], v[210:213], v[128:131]
	v_mfma_f32_16x16x32_bf16 v[116:119], v[194:197], v[218:221], v[116:119]
	v_mfma_f32_16x16x32_bf16 v[112:115], v[202:205], v[218:221], v[112:115]
	v_mfma_f32_16x16x32_bf16 v[100:103], v[194:197], v[226:229], v[100:103]
	v_mfma_f32_16x16x32_bf16 v[96:99], v[202:205], v[226:229], v[96:99]
	v_mfma_f32_16x16x32_bf16 v[84:87], v[194:197], v[234:237], v[84:87]
	v_mfma_f32_16x16x32_bf16 v[80:83], v[202:205], v[234:237], v[80:83]
	s_setprio 0
	s_barrier
	s_add_i32 s50, s67, s54
	v_lshl_add_u64 v[168:169], s[12:13], 0, v[146:147]
	s_mov_b32 m0, s50
	ds_read_b128 v[206:209], v191 offset:16384
	ds_read_b128 v[210:213], v191 offset:17408
	ds_read_b128 v[214:217], v191 offset:18432
	ds_read_b128 v[218:221], v191 offset:19456
	ds_read_b128 v[222:225], v191 offset:20480
	ds_read_b128 v[226:229], v191 offset:21504
	ds_read_b128 v[230:233], v191 offset:22528
	ds_read_b128 v[234:237], v191 offset:23552
	global_load_lds_dwordx4 v[168:169], off
	s_add_i32 m0, s50, 0x2000
	s_add_u32 s50, s12, 0x40000
	v_lshl_add_u64 v[188:189], s[12:13], 0, v[150:151]
	s_addc_u32 s51, s13, 0
	s_add_i32 s78, s72, s54
	global_load_lds_dwordx4 v[188:189], off
	v_lshl_add_u64 v[238:239], s[50:51], 0, v[146:147]
	s_mov_b32 m0, s78
	v_lshl_add_u64 v[240:241], s[14:15], 0, v[148:149]
	global_load_lds_dwordx4 v[238:239], off
	v_lshl_add_u64 v[238:239], s[50:51], 0, v[150:151]
	s_add_i32 m0, s78, 0x2000
	s_nop 0
	global_load_lds_dwordx4 v[238:239], off
	v_lshl_add_u64 v[238:239], s[14:15], 0, v[144:145]
	s_mov_b32 m0, s55
	s_nop 0
	global_load_lds_dwordx4 v[238:239], off
	s_mov_b32 m0, s58
	s_nop 0
	global_load_lds_dwordx4 v[240:241], off
	s_waitcnt vmcnt(16)
	s_waitcnt lgkmcnt(0)
	s_barrier
; #define PG8_STAGE(bufoff, gbase, voff) do { _Pragma("unroll") for (int _i = 0; _i < 2; ++_i) \
;         __builtin_amdgcn_global_load_lds((const unsigned*)((const char*)(gbase) + (voff)[_i]), (LAS unsigned*)(lds + (bufoff) + ldsw + _i * 8192), 16, 0, 0); } while (0)
; #define PG8_LDA(dst, b, h) do { _Pragma("unroll") for (int m = 0; m < 4; ++m) _Pragma("unroll") for (int k = 0; k < 2; ++k) dst[m][k] = *(const LAS bf16x8*)(lds + PG8_SA(b, h) + aoff + m * 2048 + k * 1024); } while (0)
; #define PG8_LDB(dst, b, h) do { _Pragma("unroll") for (int n = 0; n < 2; ++n) _Pragma("unroll") for (int k = 0; k < 2; ++k) dst[n][k] = *(const LAS bf16x8*)(lds + PG8_SB(b, h) + boff + n * 2048 + k * 1024); } while (0)
; #define PG8_MMA(ai, bj, At, Bt) do { __builtin_amdgcn_s_setprio(1); _Pragma("unroll") for (int m = 0; m < 4; ++m) _Pragma("unroll") for (int n = 0; n < 2; ++n) _Pragma("unroll") for (int k = 0; k < 2; ++k) \
;         acc[ai][bj][m][n] = __builtin_amdgcn_mfma_f32_16x16x32_bf16(Bt[n][k], At[m][k], acc[ai][bj][m][n], 0, 0, 0); __builtin_amdgcn_s_setprio(0); } while (0)
; #define PG8_WAIT_V(n) asm volatile("s_waitcnt vmcnt(" #n ")" ::: "memory")
; #define PG8_WAIT_L(n) asm volatile("s_waitcnt lgkmcnt(" #n ")" ::: "memory")
; #define PG8_BAR __builtin_amdgcn_s_barrier()
; #define PG8_SCHED __builtin_amdgcn_sched_barrier(0)
; template <class Epi, class Sched>
; __device__ __forceinline__ void gemm_phase(LAS unsigned char* lds, const Gemm g, const Sched& S, const Epi& E, int wave_id) {
;     ...
;             PG8_WAIT_V(8); PG8_WAIT_L(0); PG8_BAR; PG8_MMA(1, 0, At, B0); PG8_MMA(1, 1, At, B1); PG8_BAR; PG8_SCHED;
;             PG8_LDB(B0, 1, 0); PG8_LDB(B1, 1, 1); PG8_SCHED; PG8_LDA(At, 1, 0); PG8_STAGE(PG8_SA(0, 1), a2 + hstepA, voffA);
;             PG8_WAIT_V(8); PG8_WAIT_L(0); PG8_BAR; PG8_MMA(0, 0, At, B0); PG8_MMA(0, 1, At, B1); PG8_BAR; PG8_SCHED;
	s_setprio 1
	s_waitcnt lgkmcnt(0)
	v_mfma_f32_16x16x32_bf16 v[76:79], v[16:19], v[206:209], 0
	v_mfma_f32_16x16x32_bf16 v[72:75], v[32:35], v[206:209], 0
	v_mfma_f32_16x16x32_bf16 v[60:63], v[16:19], v[214:217], 0
	v_mfma_f32_16x16x32_bf16 v[56:59], v[32:35], v[214:217], 0
	v_mfma_f32_16x16x32_bf16 v[44:47], v[16:19], v[222:225], 0
	v_mfma_f32_16x16x32_bf16 v[40:43], v[32:35], v[222:225], 0
	v_mfma_f32_16x16x32_bf16 v[12:15], v[16:19], v[230:233], 0
	v_mfma_f32_16x16x32_bf16 v[8:11], v[32:35], v[230:233], 0
	v_mfma_f32_16x16x32_bf16 v[76:79], v[20:23], v[210:213], v[76:79]
	v_mfma_f32_16x16x32_bf16 v[72:75], v[36:39], v[210:213], v[72:75]
	v_mfma_f32_16x16x32_bf16 v[60:63], v[20:23], v[218:221], v[60:63]
	v_mfma_f32_16x16x32_bf16 v[56:59], v[36:39], v[218:221], v[56:59]
	v_mfma_f32_16x16x32_bf16 v[44:47], v[20:23], v[226:229], v[44:47]
	v_mfma_f32_16x16x32_bf16 v[40:43], v[36:39], v[226:229], v[40:43]
	v_mfma_f32_16x16x32_bf16 v[12:15], v[20:23], v[234:237], v[12:15]
	v_mfma_f32_16x16x32_bf16 v[8:11], v[36:39], v[234:237], v[8:11]
	s_setprio 0
	s_setprio 1
	v_mfma_f32_16x16x32_bf16 v[28:31], v[184:187], v[222:225], 0
	v_mfma_f32_16x16x32_bf16 v[24:27], v[198:201], v[222:225], 0
	v_mfma_f32_16x16x32_bf16 v[4:7], v[184:187], v[230:233], 0
	v_mfma_f32_16x16x32_bf16 v[0:3], v[198:201], v[230:233], 0
	v_mfma_f32_16x16x32_bf16 v[16:19], v[184:187], v[206:209], 0
	v_mfma_f32_16x16x32_bf16 v[20:23], v[198:201], v[206:209], 0
	v_mfma_f32_16x16x32_bf16 v[32:35], v[184:187], v[214:217], 0
	v_mfma_f32_16x16x32_bf16 v[36:39], v[198:201], v[214:217], 0
	v_mfma_f32_16x16x32_bf16 v[28:31], v[194:197], v[226:229], v[28:31]
	v_mfma_f32_16x16x32_bf16 v[24:27], v[202:205], v[226:229], v[24:27]
	v_mfma_f32_16x16x32_bf16 v[4:7], v[194:197], v[234:237], v[4:7]
	v_mfma_f32_16x16x32_bf16 v[0:3], v[202:205], v[234:237], v[0:3]
	v_mfma_f32_16x16x32_bf16 v[16:19], v[194:197], v[210:213], v[16:19]
	v_mfma_f32_16x16x32_bf16 v[20:23], v[202:205], v[210:213], v[20:23]
	v_mfma_f32_16x16x32_bf16 v[32:35], v[194:197], v[218:221], v[32:35]
	v_mfma_f32_16x16x32_bf16 v[36:39], v[202:205], v[218:221], v[36:39]
	s_setprio 0
	s_barrier
	s_add_i32 s50, 0, 0x18000
	s_add_i32 s51, 0, 0x1c000
	v_add_u32_e32 v68, s50, v171
	v_add_u32_e32 v152, s51, v171
	ds_read_b128 v[48:51], v68
	ds_read_b128 v[52:55], v68 offset:1024
	ds_read_b128 v[64:67], v68 offset:2048
	ds_read_b128 v[68:71], v68 offset:3072
	ds_read_b128 v[184:187], v152
	ds_read_b128 v[194:197], v152 offset:1024
	ds_read_b128 v[198:201], v152 offset:2048
	ds_read_b128 v[202:205], v152 offset:3072
	s_add_u32 s14, s14, 0x40000
	s_addc_u32 s15, s15, 0
	s_mov_b32 m0, s59
	v_lshl_add_u64 v[242:243], s[14:15], 0, v[144:145]
	ds_read_b128 v[206:209], v191 offset:32768
	ds_read_b128 v[210:213], v191 offset:33792
	ds_read_b128 v[214:217], v191 offset:34816
	ds_read_b128 v[218:221], v191 offset:35840
	ds_read_b128 v[222:225], v191 offset:36864
	ds_read_b128 v[226:229], v191 offset:37888
	ds_read_b128 v[230:233], v191 offset:38912
	ds_read_b128 v[234:237], v191 offset:39936
	global_load_lds_dwordx4 v[242:243], off
	v_lshl_add_u64 v[242:243], s[14:15], 0, v[148:149]
	s_mov_b32 m0, s60
	s_nop 0
	global_load_lds_dwordx4 v[242:243], off
	s_waitcnt vmcnt(8)
	s_waitcnt lgkmcnt(0)
	s_barrier
	s_setprio 1
	s_waitcnt lgkmcnt(0)
	v_mfma_f32_16x16x32_bf16 v[140:143], v[48:51], v[206:209], v[140:143]
	v_mfma_f32_16x16x32_bf16 v[136:139], v[64:67], v[206:209], v[136:139]
	v_mfma_f32_16x16x32_bf16 v[124:127], v[48:51], v[214:217], v[124:127]
	v_mfma_f32_16x16x32_bf16 v[120:123], v[64:67], v[214:217], v[120:123]
	v_mfma_f32_16x16x32_bf16 v[108:111], v[48:51], v[222:225], v[108:111]
	v_mfma_f32_16x16x32_bf16 v[104:107], v[64:67], v[222:225], v[104:107]
	v_mfma_f32_16x16x32_bf16 v[92:95], v[48:51], v[230:233], v[92:95]
	v_mfma_f32_16x16x32_bf16 v[88:91], v[64:67], v[230:233], v[88:91]
	v_mfma_f32_16x16x32_bf16 v[140:143], v[52:55], v[210:213], v[140:143]
	v_mfma_f32_16x16x32_bf16 v[136:139], v[68:71], v[210:213], v[136:139]
	v_mfma_f32_16x16x32_bf16 v[124:127], v[52:55], v[218:221], v[124:127]
	v_mfma_f32_16x16x32_bf16 v[120:123], v[68:71], v[218:221], v[120:123]
	v_mfma_f32_16x16x32_bf16 v[108:111], v[52:55], v[226:229], v[108:111]
	v_mfma_f32_16x16x32_bf16 v[104:107], v[68:71], v[226:229], v[104:107]
	v_mfma_f32_16x16x32_bf16 v[92:95], v[52:55], v[234:237], v[92:95]
	v_mfma_f32_16x16x32_bf16 v[88:91], v[68:71], v[234:237], v[88:91]
	s_setprio 0
	s_setprio 1
	v_mfma_f32_16x16x32_bf16 v[132:135], v[184:187], v[206:209], v[132:135]
	v_mfma_f32_16x16x32_bf16 v[128:131], v[198:201], v[206:209], v[128:131]
	v_mfma_f32_16x16x32_bf16 v[116:119], v[184:187], v[214:217], v[116:119]
	v_mfma_f32_16x16x32_bf16 v[112:115], v[198:201], v[214:217], v[112:115]
	v_mfma_f32_16x16x32_bf16 v[100:103], v[184:187], v[222:225], v[100:103]
	v_mfma_f32_16x16x32_bf16 v[96:99], v[198:201], v[222:225], v[96:99]
	v_mfma_f32_16x16x32_bf16 v[84:87], v[184:187], v[230:233], v[84:87]
	v_mfma_f32_16x16x32_bf16 v[80:83], v[198:201], v[230:233], v[80:83]
	v_mfma_f32_16x16x32_bf16 v[132:135], v[194:197], v[210:213], v[132:135]
	v_mfma_f32_16x16x32_bf16 v[128:131], v[202:205], v[210:213], v[128:131]
	v_mfma_f32_16x16x32_bf16 v[116:119], v[194:197], v[218:221], v[116:119]
	v_mfma_f32_16x16x32_bf16 v[112:115], v[202:205], v[218:221], v[112:115]
	v_mfma_f32_16x16x32_bf16 v[100:103], v[194:197], v[226:229], v[100:103]
	v_mfma_f32_16x16x32_bf16 v[96:99], v[202:205], v[226:229], v[96:99]
	v_mfma_f32_16x16x32_bf16 v[84:87], v[194:197], v[234:237], v[84:87]
	v_mfma_f32_16x16x32_bf16 v[80:83], v[202:205], v[234:237], v[80:83]
	s_setprio 0
	s_barrier
; #define PG8_STAGE(bufoff, gbase, voff) do { _Pragma("unroll") for (int _i = 0; _i < 2; ++_i) \
;         __builtin_amdgcn_global_load_lds((const unsigned*)((const char*)(gbase) + (voff)[_i]), (LAS unsigned*)(lds + (bufoff) + ldsw + _i * 8192), 16, 0, 0); } while (0)
; #define PG8_LDA(dst, b, h) do { _Pragma("unroll") for (int m = 0; m < 4; ++m) _Pragma("unroll") for (int k = 0; k < 2; ++k) dst[m][k] = *(const LAS bf16x8*)(lds + PG8_SA(b, h) + aoff + m * 2048 + k * 1024); } while (0)
; #define PG8_MMA(ai, bj, At, Bt) do { __builtin_amdgcn_s_setprio(1); _Pragma("unroll") for (int m = 0; m < 4; ++m) _Pragma("unroll") for (int n = 0; n < 2; ++n) _Pragma("unroll") for (int k = 0; k < 2; ++k) \
;         acc[ai][bj][m][n] = __builtin_amdgcn_mfma_f32_16x16x32_bf16(Bt[n][k], At[m][k], acc[ai][bj][m][n], 0, 0, 0); __builtin_amdgcn_s_setprio(0); } while (0)
; #define PG8_WAIT_V(n) asm volatile("s_waitcnt vmcnt(" #n ")" ::: "memory")
; #define PG8_WAIT_L(n) asm volatile("s_waitcnt lgkmcnt(" #n ")" ::: "memory")
; #define PG8_BAR __builtin_amdgcn_s_barrier()
; #define PG8_SCHED __builtin_amdgcn_sched_barrier(0)
; template <class Epi, class Sched>
; __device__ __forceinline__ void gemm_phase(LAS unsigned char* lds, const Gemm g, const Sched& S, const Epi& E, int wave_id) {
;     ...
;             PG8_LDA(At, 1, 1); PG8_STAGE(PG8_SB(1, 0), b3, voffB); PG8_STAGE(PG8_SB(1, 1), b3 + hstepB, voffB); PG8_STAGE(PG8_SA(1, 0), a3, voffA);
;             PG8_WAIT_V(8); PG8_WAIT_L(0); PG8_BAR; PG8_MMA(1, 0, At, B0); PG8_MMA(1, 1, At, B1); PG8_BAR; PG8_SCHED;
	s_add_i32 s14, s50, s54
	v_lshl_add_u64 v[168:169], v[168:169], 0, s[22:23]
	s_mov_b32 m0, s14
	ds_read_b128 v[206:209], v191 offset:49152
	ds_read_b128 v[210:213], v191 offset:50176
	ds_read_b128 v[214:217], v191 offset:51200
	ds_read_b128 v[218:221], v191 offset:52224
	ds_read_b128 v[222:225], v191 offset:53248
	ds_read_b128 v[226:229], v191 offset:54272
	ds_read_b128 v[230:233], v191 offset:55296
	ds_read_b128 v[234:237], v191 offset:56320
	global_load_lds_dwordx4 v[168:169], off
	s_add_i32 m0, s14, 0x2000
	s_add_u32 s12, s12, 0x40080
	v_lshl_add_u64 v[168:169], v[188:189], 0, s[22:23]
	s_addc_u32 s13, s13, 0
	s_add_i32 s14, s51, s54
	global_load_lds_dwordx4 v[168:169], off
	v_lshl_add_u64 v[168:169], s[12:13], 0, v[146:147]
	s_mov_b32 m0, s14
	s_nop 0
	global_load_lds_dwordx4 v[168:169], off
	v_lshl_add_u64 v[168:169], s[12:13], 0, v[150:151]
	s_add_i32 m0, s14, 0x2000
	s_nop 0
	global_load_lds_dwordx4 v[168:169], off
	v_lshl_add_u64 v[168:169], v[238:239], 0, s[22:23]
	s_mov_b32 m0, s62
	s_nop 0
	global_load_lds_dwordx4 v[168:169], off
	v_lshl_add_u64 v[168:169], v[240:241], 0, s[22:23]
	s_mov_b32 m0, s63
	s_nop 0
	global_load_lds_dwordx4 v[168:169], off
	s_waitcnt vmcnt(8)
	s_waitcnt lgkmcnt(0)
	s_barrier
	s_setprio 1
	s_waitcnt lgkmcnt(0)
	v_mfma_f32_16x16x32_bf16 v[76:79], v[48:51], v[206:209], v[76:79]
	v_mfma_f32_16x16x32_bf16 v[72:75], v[64:67], v[206:209], v[72:75]
	v_mfma_f32_16x16x32_bf16 v[60:63], v[48:51], v[214:217], v[60:63]
	v_mfma_f32_16x16x32_bf16 v[56:59], v[64:67], v[214:217], v[56:59]
	v_mfma_f32_16x16x32_bf16 v[44:47], v[48:51], v[222:225], v[44:47]
	v_mfma_f32_16x16x32_bf16 v[40:43], v[64:67], v[222:225], v[40:43]
	v_mfma_f32_16x16x32_bf16 v[12:15], v[48:51], v[230:233], v[12:15]
	v_mfma_f32_16x16x32_bf16 v[8:11], v[64:67], v[230:233], v[8:11]
	v_mfma_f32_16x16x32_bf16 v[76:79], v[52:55], v[210:213], v[76:79]
	v_mfma_f32_16x16x32_bf16 v[72:75], v[68:71], v[210:213], v[72:75]
	v_mfma_f32_16x16x32_bf16 v[60:63], v[52:55], v[218:221], v[60:63]
	v_mfma_f32_16x16x32_bf16 v[56:59], v[68:71], v[218:221], v[56:59]
	v_mfma_f32_16x16x32_bf16 v[44:47], v[52:55], v[226:229], v[44:47]
	v_mfma_f32_16x16x32_bf16 v[40:43], v[68:71], v[226:229], v[40:43]
	v_mfma_f32_16x16x32_bf16 v[12:15], v[52:55], v[234:237], v[12:15]
	v_mfma_f32_16x16x32_bf16 v[8:11], v[68:71], v[234:237], v[8:11]
	s_setprio 0
	s_setprio 1
	v_mfma_f32_16x16x32_bf16 v[16:19], v[184:187], v[206:209], v[16:19]
	v_mfma_f32_16x16x32_bf16 v[68:71], v[194:197], v[210:213], v[16:19]
	v_mfma_f32_16x16x32_bf16 v[16:19], v[198:201], v[206:209], v[20:23]
	v_mfma_f32_16x16x32_bf16 v[64:67], v[202:205], v[210:213], v[16:19]
	v_mfma_f32_16x16x32_bf16 v[16:19], v[184:187], v[214:217], v[32:35]
	v_mfma_f32_16x16x32_bf16 v[52:55], v[194:197], v[218:221], v[16:19]
	v_mfma_f32_16x16x32_bf16 v[16:19], v[198:201], v[214:217], v[36:39]
	v_mfma_f32_16x16x32_bf16 v[48:51], v[202:205], v[218:221], v[16:19]
	v_mfma_f32_16x16x32_bf16 v[16:19], v[184:187], v[222:225], v[28:31]
	v_mfma_f32_16x16x32_bf16 v[28:31], v[194:197], v[226:229], v[16:19]
	v_mfma_f32_16x16x32_bf16 v[16:19], v[198:201], v[222:225], v[24:27]
	v_mfma_f32_16x16x32_bf16 v[4:7], v[184:187], v[230:233], v[4:7]
	v_mfma_f32_16x16x32_bf16 v[0:3], v[198:201], v[230:233], v[0:3]
	v_mfma_f32_16x16x32_bf16 v[24:27], v[202:205], v[226:229], v[16:19]
	v_mfma_f32_16x16x32_bf16 v[4:7], v[194:197], v[234:237], v[4:7]
	v_mfma_f32_16x16x32_bf16 v[0:3], v[202:205], v[234:237], v[0:3]
	s_setprio 0
	s_barrier
	s_add_i32 s45, s45, 2
	s_add_u32 s10, s10, 0x100
	s_addc_u32 s11, s11, 0
	s_add_u32 s33, s33, 0x100
	s_addc_u32 s39, s39, 0
	s_cmp_gt_u32 s45, 13

; __device__ __forceinline__ float sigmoidf_(float z) { return __builtin_amdgcn_rcpf(1.0f + __builtin_amdgcn_exp2f(-1.4426950408889634f * z)); }
; __device__ __forceinline__ u32x4 pack8(const float (&f)[8]) { u32x4 w; w.x = pk2(f[0], f[1]); w.y = pk2(f[2], f[3]); w.z = pk2(f[4], f[5]); w.w = pk2(f[6], f[7]); return w; }
;     __device__ __forceinline__ void load(Pre& p, const pg8::Unit& u, int ai, int m, int wr, int wc, int fr, int fq) const {
;         const int row = u.pm * 256 + ai * 128 + wr * 64 + m * 16 + fr;
;         if (MODE == EM_PROJ || MODE == EM_GATES) p.rs = ((const float*)(ws + WS_RINV0))[row];
;     __device__ __forceinline__ float compute(const Pre& p, f32x4 (&acc)[2][2][4][2], const f32x4 (&cv)[2][2], const pg8::Unit& u, int ai, int m, int wr, int wc, int fr, int fq) const {
;     ...
;                 } else {
;                     const int col = (pn - 18) * 256 + ct; float w[8];
; #pragma unroll
;                     for (int j = 0; j < 8; ++j) { const float z = v[j] * rs; w[j] = z * sigmoidf_(z); }
;                     __builtin_nontemporal_store(pack8(w), (u32x4*)((bf16_t*)(ws + WS_ZS) + (size_t)row * 512 + col));
.LBB0_257:
	s_lshl_b32 s2, s8, 8
	s_add_i32 s2, s2, s61
	v_or_b32_e32 v168, s2, v167
	v_ashrrev_i32_e32 v169, 31, v168
	v_add_u32_e32 v186, 0x80, v168
	v_lshl_add_u64 v[184:185], v[168:169], 2, s[26:27]
	v_ashrrev_i32_e32 v187, 31, v186
	v_lshl_add_u64 v[186:187], v[186:187], 2, s[26:27]
	v_mov_b32_e32 v182, v244
	v_mov_b32_e32 v180, v245
	v_mov_b32_e32 v178, v246
	v_mov_b32_e32 v176, v247
	v_mov_b32_e32 v174, v248
	v_mov_b32_e32 v172, v249
	v_mov_b32_e32 v170, v250
	v_mov_b32_e32 v166, v251
	s_cmp_gt_u32 s6, 3
	s_cselect_b64 s[10:11], -1, 0
	s_cmp_gt_i32 s6, 15
	v_add_lshl_u32 v184, v177, s39, 7
	s_cselect_b64 s[12:13], -1, 0
	s_cmp_gt_u32 s6, 17
	v_add_u32_e32 v152, s39, v175
	s_mov_b64 s[8:9], -1
	v_and_b32_e32 v203, 0x7fffb800, v184
	v_lshlrev_b64 v[184:185], 10, v[168:169]
	s_cselect_b64 s[14:15], -1, 0
	s_ashr_i32 s33, s2, 4
	s_and_b64 vcc, exec, s[12:13]
	s_waitcnt vmcnt(0)
	v_mul_f32_e32 v186, v140, v182
	s_cbranch_vccz .LBB0_263
	s_and_b64 vcc, exec, s[14:15]
	s_cbranch_vccz .LBB0_260
	v_mul_f32_e32 v140, 0xbfb8aa3b, v186
	v_mul_f32_e32 v187, v141, v182
	v_exp_f32_e32 v140, v140
	v_mul_f32_e32 v168, 0xbfb8aa3b, v187
	v_exp_f32_e32 v169, v168
	v_pk_mul_f32 v[188:189], v[142:143], v[182:183] op_sel_hi:[1,0]
	v_add_f32_e32 v140, 1.0, v140
	v_rcp_f32_e32 v168, v140
	v_add_f32_e32 v140, 1.0, v169
	v_mul_f32_e32 v169, 0xbfb8aa3b, v188
	v_exp_f32_e32 v193, v169
	v_mul_f32_e32 v169, 0xbfb8aa3b, v189
	v_exp_f32_e32 v195, v169
	v_pk_mul_f32 v[196:197], v[136:137], v[182:183] op_sel_hi:[1,0]
	v_rcp_f32_e32 v169, v140
	v_add_f32_e32 v140, 1.0, v193
	v_mul_f32_e32 v193, 0xbfb8aa3b, v196
	v_rcp_f32_e32 v194, v140
	v_add_f32_e32 v140, 1.0, v195
	v_exp_f32_e32 v193, v193
	v_mul_f32_e32 v195, 0xbfb8aa3b, v197
	v_exp_f32_e32 v199, v195
	v_pk_mul_f32 v[200:201], v[138:139], v[182:183] op_sel_hi:[1,0]
	v_rcp_f32_e32 v195, v140
	v_add_f32_e32 v140, 1.0, v193
	v_mul_f32_e32 v193, 0xbfb8aa3b, v200
	v_rcp_f32_e32 v198, v140
	v_add_f32_e32 v140, 1.0, v199
	v_exp_f32_e32 v193, v193
	v_mul_f32_e32 v199, 0xbfb8aa3b, v201
	v_exp_f32_e32 v202, v199
	v_rcp_f32_e32 v199, v140
	v_add_f32_e32 v140, 1.0, v193
	v_rcp_f32_e32 v204, v140
	v_add_f32_e32 v140, 1.0, v202
	v_rcp_f32_e32 v205, v140
	v_pk_mul_f32 v[168:169], v[186:187], v[168:169]
	v_pk_mul_f32 v[188:189], v[188:189], v[194:195]
	v_pk_mul_f32 v[196:197], v[196:197], v[198:199]
	v_pk_mul_f32 v[198:199], v[200:201], v[204:205]
	v_cvt_pk_bf16_f32 v194, v168, v169
	v_lshl_add_u64 v[168:169], s[28:29], 0, v[184:185]
	v_cvt_pk_bf16_f32 v195, v188, v189
	v_cvt_pk_bf16_f32 v196, v196, v197
	v_cvt_pk_bf16_f32 v197, v198, v199
	v_lshl_add_u64 v[168:169], v[152:153], 1, v[168:169]
	global_store_dwordx4 v[168:169], v[194:197], off nt
	s_mov_b64 s[8:9], 0
